# speedup vs baseline: 1.0412x; 1.0078x over previous
; DI float bflo(unsigned w) { return __uint_as_float(w << 16); }
; DI float bfhi(unsigned w) { return __uint_as_float(w & 0xffff0000u); }
; DI void ln_rows(const float* __restrict__ xres, const bf16_t* __restrict__ xres_b, const bf16_t* __restrict__ mb, float* __restrict__ x1f, bf16_t* __restrict__ xb, const float* __restrict__ g, const float* __restrict__ bta) {
;     ...
;         for (int j = 0; j < 4; ++j) {
;             f32x4 xv; if (xres_b) { const u32x2 xw_ = *(const u32x2*)(xres_b + (size_t)r * DM + 4 * lane + 256 * j); xv = (f32x4){bflo(xw_.x), bfhi(xw_.x), bflo(xw_.y), bfhi(xw_.y)}; } else xv = *(const f32x4*)(xr + 256 * j);
;             const u32x2 mv = *(const u32x2*)(mr + 256 * j);
;             v[j].x = ALPHA * xv.x + bflo(mv.x); v[j].y = ALPHA * xv.y + bfhi(mv.x); v[j].z = ALPHA * xv.z + bflo(mv.y); v[j].w = ALPHA * xv.w + bfhi(mv.y);
.LBB0_111:
	s_waitcnt vmcnt(0)
	s_andn2_b64 vcc, exec, s[12:13]
	s_cbranch_vccnz .LBB0_111b
	v_lshlrev_b32_e32 v36, 16, v38
	v_and_b32_e32 v37, 0xffff0000, v38
	v_lshlrev_b32_e32 v38, 16, v39
	v_and_b32_e32 v39, 0xffff0000, v39
	v_lshlrev_b32_e32 v40, 16, v42
	v_and_b32_e32 v41, 0xffff0000, v42
	v_lshlrev_b32_e32 v42, 16, v43
	v_and_b32_e32 v43, 0xffff0000, v43
	v_lshlrev_b32_e32 v44, 16, v46
	v_and_b32_e32 v45, 0xffff0000, v46
	v_lshlrev_b32_e32 v46, 16, v47
	v_and_b32_e32 v47, 0xffff0000, v47
	v_lshlrev_b32_e32 v32, 16, v34
	v_and_b32_e32 v33, 0xffff0000, v34
	v_lshlrev_b32_e32 v34, 16, v35
	v_and_b32_e32 v35, 0xffff0000, v35
; DI unsigned pk2(float lo, float hi) { const f32x2 v = {lo, hi}; return __builtin_bit_cast(unsigned, __builtin_convertvector(v, bf16x2_t)); }
; DI float bflo(unsigned w) { return __uint_as_float(w << 16); }
; DI float bfhi(unsigned w) { return __uint_as_float(w & 0xffff0000u); }
; DI void ln_rows(const float* __restrict__ xres, const bf16_t* __restrict__ xres_b, const bf16_t* __restrict__ mb, float* __restrict__ x1f, bf16_t* __restrict__ xb, const float* __restrict__ g, const float* __restrict__ bta) {
;     ...
;     for (int r = gw; r < T_TOK; r += nw) {
;         const float* xr = xres + (size_t)r * DM + 4 * lane;
;         const bf16_t* mr = mb + (size_t)r * DM + 4 * lane;
;         f32x4 v[4]; float s = 0.f;
; #pragma unroll
;         for (int j = 0; j < 4; ++j) {
;             f32x4 xv; if (xres_b) { const u32x2 xw_ = *(const u32x2*)(xres_b + (size_t)r * DM + 4 * lane + 256 * j); xv = (f32x4){bflo(xw_.x), bfhi(xw_.x), bflo(xw_.y), bfhi(xw_.y)}; } else xv = *(const f32x4*)(xr + 256 * j);
;             const u32x2 mv = *(const u32x2*)(mr + 256 * j);
;             v[j].x = ALPHA * xv.x + bflo(mv.x); v[j].y = ALPHA * xv.y + bfhi(mv.x); v[j].z = ALPHA * xv.z + bflo(mv.y); v[j].w = ALPHA * xv.w + bfhi(mv.y);
;             s += (v[j].x + v[j].y) + (v[j].z + v[j].w);
;         }
;         const float mean = wave_sum(s) * (1.f / DM); float q = 0.f;
; #pragma unroll
;         for (int j = 0; j < 4; ++j) { v[j] = v[j] - mean; q += (v[j].x * v[j].x + v[j].y * v[j].y) + (v[j].z * v[j].z + v[j].w * v[j].w); }
;         const float rstd = rsqrtf(wave_sum(q) * (1.f / DM) + LN_EPS);
; #pragma unroll
;         for (int j = 0; j < 4; ++j) {
;             const f32x4 o = v[j] * rstd * g4[j] + b4[j];
;             u32x2 wv; wv.x = pk2(o.x, o.y); wv.y = pk2(o.z, o.w);
;             *(u32x2*)(xb + (size_t)r * PA + 4 * lane + 256 * j) = wv;
;         }
;     }
.LBB0_111b:
	v_lshlrev_b32_e32 v52, 16, v54
	v_and_b32_e32 v53, 0xffff0000, v54
	v_pk_fma_f32 v[52:53], v[36:37], s[78:79], v[52:53] op_sel_hi:[1,0,1]
	v_lshlrev_b32_e32 v36, 16, v55
	v_and_b32_e32 v37, 0xffff0000, v55
	v_pk_fma_f32 v[54:55], v[38:39], s[78:79], v[36:37] op_sel_hi:[1,0,1]
	v_add_f32_e32 v37, v52, v53
	v_add_f32_e32 v36, v54, v55
	v_add_f32_e32 v36, v37, v36
	v_add_f32_e32 v66, 0, v36
	v_lshlrev_b32_e32 v36, 16, v56
	v_and_b32_e32 v37, 0xffff0000, v56
	v_lshlrev_b32_e32 v38, 16, v57
	v_and_b32_e32 v39, 0xffff0000, v57
	v_pk_fma_f32 v[36:37], v[40:41], s[78:79], v[36:37] op_sel_hi:[1,0,1]
	v_pk_fma_f32 v[38:39], v[42:43], s[78:79], v[38:39] op_sel_hi:[1,0,1]
	v_add_f32_e32 v41, v36, v37
	v_add_f32_e32 v40, v38, v39
	v_add_f32_e32 v40, v41, v40
	v_add_f32_e32 v56, v66, v40
	v_lshlrev_b32_e32 v40, 16, v58
	v_and_b32_e32 v41, 0xffff0000, v58
	v_lshlrev_b32_e32 v42, 16, v59
	v_and_b32_e32 v43, 0xffff0000, v59
	v_pk_fma_f32 v[40:41], v[44:45], s[78:79], v[40:41] op_sel_hi:[1,0,1]
	v_pk_fma_f32 v[42:43], v[46:47], s[78:79], v[42:43] op_sel_hi:[1,0,1]
	v_add_f32_e32 v45, v40, v41
	v_add_f32_e32 v44, v42, v43
	v_add_f32_e32 v44, v45, v44
	s_mov_b32 s0, 0x4b01000
	v_add_f32_e32 v56, v56, v44
	v_add_co_u32_e32 v44, vcc, s0, v50
	s_mov_b32 s0, 0xdb01000
	s_nop 0
	v_addc_co_u32_e32 v45, vcc, 0, v51, vcc
	global_load_dwordx2 v[44:45], v[44:45], off offset:1536
	s_add_i32 s2, s2, s90
	s_add_u32 s4, s4, s74
	s_addc_u32 s5, s5, s75
	s_add_u32 s6, s6, s74
	s_addc_u32 s7, s7, s75
	v_lshl_add_u64 v[48:49], v[48:49], 0, s[10:11]
	s_cmpk_gt_i32 s2, 0x7fff
	s_waitcnt vmcnt(0)
	v_lshlrev_b32_e32 v46, 16, v44
	v_and_b32_e32 v47, 0xffff0000, v44
	v_lshlrev_b32_e32 v44, 16, v45
	v_and_b32_e32 v45, 0xffff0000, v45
	v_pk_fma_f32 v[32:33], v[32:33], s[78:79], v[46:47] op_sel_hi:[1,0,1]
	v_pk_fma_f32 v[34:35], v[34:35], s[78:79], v[44:45] op_sel_hi:[1,0,1]
	v_mov_b32_e32 v44, v32
	v_mov_b32_e32 v45, v34
	v_mov_b32_e32 v46, v33
	v_mov_b32_e32 v47, v35
	v_pk_add_f32 v[44:45], v[44:45], v[46:47]
	s_nop 0
	v_add_f32_e32 v44, v44, v45
	v_add_f32_e32 v44, v56, v44
	s_waitcnt lgkmcnt(0)
	s_nop 1
	v_add_f32_dpp v44, v44, v44 quad_perm:[1,0,3,2] row_mask:0xf bank_mask:0xf
	s_nop 1
	v_add_f32_dpp v44, v44, v44 quad_perm:[2,3,0,1] row_mask:0xf bank_mask:0xf
	s_nop 1
	v_add_f32_dpp v44, v44, v44 row_half_mirror row_mask:0xf bank_mask:0xf
	s_nop 1
	v_add_f32_dpp v44, v44, v44 row_mirror row_mask:0xf bank_mask:0xf
	s_nop 1
	v_add_f32_dpp v44, v44, v44 row_bcast:15 row_mask:0xa bank_mask:0xf
	s_nop 1
	v_add_f32_dpp v44, v44, v44 row_bcast:31 row_mask:0xc bank_mask:0xf
	s_nop 0
	v_readlane_b32 vcc_lo, v44, 63
	s_nop 1
	v_mov_b32_e32 v66, vcc_lo
	v_fmamk_f32 v53, v66, 0xba800000, v53
	v_fmac_f32_e32 v52, 0xba800000, v66
	v_fmamk_f32 v55, v66, 0xba800000, v55
	v_fmac_f32_e32 v54, 0xba800000, v66
	v_pk_mul_f32 v[44:45], v[54:55], v[54:55]
	v_pk_mul_f32 v[46:47], v[52:53], v[52:53]
	v_fmamk_f32 v37, v66, 0xba800000, v37
	v_pk_mov_b32 v[56:57], v[46:47], v[44:45] op_sel:[1,0]
	v_mov_b32_e32 v47, v45
	v_pk_add_f32 v[44:45], v[56:57], v[46:47]
	v_fmac_f32_e32 v36, 0xba800000, v66
	v_fmamk_f32 v39, v66, 0xba800000, v39
	v_fmac_f32_e32 v38, 0xba800000, v66
	v_pk_add_f32 v[44:45], v[44:45], v[44:45] op_sel_hi:[0,1]
	v_pk_mul_f32 v[46:47], v[38:39], v[38:39]
	v_pk_mul_f32 v[56:57], v[36:37], v[36:37]
	v_fmac_f32_e32 v40, 0xba800000, v66
	v_pk_mov_b32 v[58:59], v[56:57], v[46:47] op_sel:[1,0]
	v_mov_b32_e32 v57, v47
	v_fmamk_f32 v41, v66, 0xba800000, v41
	v_fmac_f32_e32 v42, 0xba800000, v66
	v_mul_f32_e32 v44, v40, v40
	v_pk_add_f32 v[46:47], v[58:59], v[56:57]
	v_fmamk_f32 v43, v66, 0xba800000, v43
	v_pk_fma_f32 v[56:57], v[40:41], v[40:41], v[44:45] op_sel_hi:[1,1,0]
	v_mul_f32_e32 v44, v42, v42
	v_pk_add_f32 v[46:47], v[46:47], v[46:47] op_sel_hi:[0,1]
	v_pk_fma_f32 v[58:59], v[42:43], v[42:43], v[44:45] op_sel_hi:[1,1,0]
	v_fmamk_f32 v35, v66, 0xba800000, v35
	v_fmac_f32_e32 v34, 0xba800000, v66
	v_fmamk_f32 v33, v66, 0xba800000, v33
	v_fmac_f32_e32 v32, 0xba800000, v66
	v_mul_f32_e32 v56, v32, v32
	v_mul_f32_e32 v58, v33, v33
	v_mul_f32_e32 v44, v34, v34
	v_mul_f32_e32 v46, v35, v35
	v_pk_add_f32 v[56:57], v[56:57], v[58:59]
	v_pk_add_f32 v[44:45], v[44:45], v[46:47]
	s_nop 0
	v_pk_add_f32 v[44:45], v[56:57], v[44:45]
	s_nop 0
	v_add_f32_e32 v44, v44, v45
	s_waitcnt lgkmcnt(0)
	s_nop 1
	v_add_f32_dpp v44, v44, v44 quad_perm:[1,0,3,2] row_mask:0xf bank_mask:0xf
	s_nop 1
	v_add_f32_dpp v44, v44, v44 quad_perm:[2,3,0,1] row_mask:0xf bank_mask:0xf
	s_nop 1
	v_add_f32_dpp v44, v44, v44 row_half_mirror row_mask:0xf bank_mask:0xf
	s_nop 1
	v_add_f32_dpp v44, v44, v44 row_mirror row_mask:0xf bank_mask:0xf
	s_nop 1
	v_add_f32_dpp v44, v44, v44 row_bcast:15 row_mask:0xa bank_mask:0xf
	s_nop 1
	v_add_f32_dpp v44, v44, v44 row_bcast:31 row_mask:0xc bank_mask:0xf
	s_nop 0
	v_readlane_b32 vcc_lo, v44, 63
	s_nop 1
	v_mov_b32_e32 v44, vcc_lo
	v_fmamk_f32 v44, v44, 0x3a800000, v195
	v_cmp_gt_f32_e32 vcc, s69, v44
	v_mul_f32_e32 v45, 0x4b800000, v44
	s_nop 0
	v_cndmask_b32_e32 v44, v44, v45, vcc
	v_rsq_f32_e32 v44, v44
	s_nop 0
	v_mul_f32_e32 v45, 0x45800000, v44
	v_cndmask_b32_e32 v44, v44, v45, vcc
	v_pk_mul_f32 v[36:37], v[36:37], v[44:45] op_sel_hi:[1,0]
	v_pk_mul_f32 v[38:39], v[38:39], v[44:45] op_sel_hi:[1,0]
	v_add_co_u32_e32 v50, vcc, s0, v50
	v_pk_fma_f32 v[38:39], v[6:7], v[38:39], v[14:15]
	v_pk_fma_f32 v[36:37], v[4:5], v[36:37], v[12:13]
	v_addc_co_u32_e32 v51, vcc, 0, v51, vcc
	v_cvt_pk_bf16_f32 v36, v36, v37
	v_cvt_pk_bf16_f32 v37, v38, v39
	v_pk_mul_f32 v[46:47], v[52:53], v[44:45] op_sel_hi:[1,0]
	v_pk_mul_f32 v[52:53], v[54:55], v[44:45] op_sel_hi:[1,0]
	global_store_dwordx2 v[50:51], v[36:37], off offset:512
	v_pk_mul_f32 v[36:37], v[40:41], v[44:45] op_sel_hi:[1,0]
	v_pk_mul_f32 v[38:39], v[42:43], v[44:45] op_sel_hi:[1,0]
	v_pk_mul_f32 v[32:33], v[32:33], v[44:45] op_sel_hi:[1,0]
	v_pk_mul_f32 v[34:35], v[34:35], v[44:45] op_sel_hi:[1,0]
	v_pk_fma_f32 v[52:53], v[2:3], v[52:53], v[10:11]
	v_pk_fma_f32 v[46:47], v[0:1], v[46:47], v[8:9]
	v_pk_fma_f32 v[38:39], v[18:19], v[38:39], v[26:27]
	v_pk_fma_f32 v[36:37], v[16:17], v[36:37], v[24:25]
	v_pk_fma_f32 v[34:35], v[22:23], v[34:35], v[30:31]
	v_pk_fma_f32 v[32:33], v[20:21], v[32:33], v[28:29]
	v_cvt_pk_bf16_f32 v46, v46, v47
	v_cvt_pk_bf16_f32 v47, v52, v53
	v_cvt_pk_bf16_f32 v36, v36, v37
	v_cvt_pk_bf16_f32 v37, v38, v39
	v_cvt_pk_bf16_f32 v32, v32, v33
	v_cvt_pk_bf16_f32 v33, v34, v35
	global_store_dwordx2 v[50:51], v[46:47], off
	global_store_dwordx2 v[50:51], v[36:37], off offset:1024
	global_store_dwordx2 v[50:51], v[32:33], off offset:1536
	s_cbranch_scc1 .LBB0_128
.LBB0_112:
	v_cndmask_b32_e64 v32, 0, 1, s[12:13]
	v_lshl_add_u64 v[52:53], s[6:7], 0, v[128:129]
	v_cmp_ne_u32_e64 s[0:1], 1, v32
	s_andn2_b64 vcc, exec, s[12:13]
	s_mov_b64 s[8:9], -1
	s_cbranch_vccnz .LBB0_114
	global_load_dwordx2 v[38:39], v[52:53], off
	s_mov_b64 s[8:9], 0

; DI float bflo(unsigned w) { return __uint_as_float(w << 16); }
; DI float bfhi(unsigned w) { return __uint_as_float(w & 0xffff0000u); }
; DI void ln_rows(const float* __restrict__ xres, const bf16_t* __restrict__ xres_b, const bf16_t* __restrict__ mb, float* __restrict__ x1f, bf16_t* __restrict__ xb, const float* __restrict__ g, const float* __restrict__ bta) {
;     ...
;         for (int j = 0; j < 4; ++j) {
;             f32x4 xv; if (xres_b) { const u32x2 xw_ = *(const u32x2*)(xres_b + (size_t)r * DM + 4 * lane + 256 * j); xv = (f32x4){bflo(xw_.x), bfhi(xw_.x), bflo(xw_.y), bfhi(xw_.y)}; } else xv = *(const f32x4*)(xr + 256 * j);
;             const u32x2 mv = *(const u32x2*)(mr + 256 * j);
.LBB0_116:
	v_lshl_add_u64 v[50:51], s[4:5], 0, v[128:129]
	v_add_co_u32_e32 v32, vcc, 0x4b01000, v50
	s_mov_b64 s[8:9], -1
	s_nop 0
	v_addc_co_u32_e32 v33, vcc, 0, v51, vcc
	global_load_dwordx2 v[54:55], v[32:33], off
	s_and_b64 vcc, exec, s[0:1]
	s_cbranch_vccnz .LBB0_118
	global_load_dwordx2 v[42:43], v[52:53], off offset:512
	s_mov_b64 s[8:9], 0

; DI float bflo(unsigned w) { return __uint_as_float(w << 16); }
; DI float bfhi(unsigned w) { return __uint_as_float(w & 0xffff0000u); }
; DI void ln_rows(const float* __restrict__ xres, const bf16_t* __restrict__ xres_b, const bf16_t* __restrict__ mb, float* __restrict__ x1f, bf16_t* __restrict__ xb, const float* __restrict__ g, const float* __restrict__ bta) {
;     ...
;         for (int j = 0; j < 4; ++j) {
;             f32x4 xv; if (xres_b) { const u32x2 xw_ = *(const u32x2*)(xres_b + (size_t)r * DM + 4 * lane + 256 * j); xv = (f32x4){bflo(xw_.x), bfhi(xw_.x), bflo(xw_.y), bfhi(xw_.y)}; } else xv = *(const f32x4*)(xr + 256 * j);
;             const u32x2 mv = *(const u32x2*)(mr + 256 * j);
.LBB0_120:
	v_add_co_u32_e32 v32, vcc, 0x4b01000, v50
	s_mov_b64 s[8:9], -1
	s_nop 0
	v_addc_co_u32_e32 v33, vcc, 0, v51, vcc
	global_load_dwordx2 v[56:57], v[32:33], off offset:512
	s_and_b64 vcc, exec, s[0:1]
	s_cbranch_vccnz .LBB0_122
	global_load_dwordx2 v[46:47], v[52:53], off offset:1024
	s_mov_b64 s[8:9], 0

; DI float bflo(unsigned w) { return __uint_as_float(w << 16); }
; DI float bfhi(unsigned w) { return __uint_as_float(w & 0xffff0000u); }
; DI void ln_rows(const float* __restrict__ xres, const bf16_t* __restrict__ xres_b, const bf16_t* __restrict__ mb, float* __restrict__ x1f, bf16_t* __restrict__ xb, const float* __restrict__ g, const float* __restrict__ bta) {
;     ...
;         for (int j = 0; j < 4; ++j) {
;             f32x4 xv; if (xres_b) { const u32x2 xw_ = *(const u32x2*)(xres_b + (size_t)r * DM + 4 * lane + 256 * j); xv = (f32x4){bflo(xw_.x), bfhi(xw_.x), bflo(xw_.y), bfhi(xw_.y)}; } else xv = *(const f32x4*)(xr + 256 * j);
;             const u32x2 mv = *(const u32x2*)(mr + 256 * j);
.LBB0_124:
	v_add_co_u32_e32 v32, vcc, 0x4b01000, v50
	s_nop 1
	v_addc_co_u32_e32 v33, vcc, 0, v51, vcc
	global_load_dwordx2 v[58:59], v[32:33], off offset:1024
	s_and_b64 vcc, exec, s[0:1]
	s_mov_b64 s[0:1], -1
	s_cbranch_vccnz .LBB0_126
	global_load_dwordx2 v[34:35], v[52:53], off offset:1536
	s_mov_b64 s[0:1], 0
.LBB0_126:
	s_andn2_b64 vcc, exec, s[0:1]
	s_cbranch_vccnz .LBB0_111
	global_load_dwordx4 v[32:35], v[48:49], off
	s_branch .LBB0_111
